# NSA top-k ranking loop: single 64-bit key compare (score bits, 63-index) + carry-add per candidate instead of gt/eq/mask/cndmask/add3
# speedup vs baseline: 1.1621x; 1.0033x over previous
; DI void nsa_item(const Params& p, int l_, int item, char* lds, int dry) {
;     ...
;       const float sc = forced ? 1e6f : (valid ? imp[q * 65 + j] : -1.f);
;       int rank = 0;
; #pragma unroll
;       for (int i = 0; i < 64; ++i) {
;         const float si = __int_as_float(__builtin_amdgcn_readlane(__float_as_int(sc), i));
;         rank += ((si > sc) || (si == sc && i < j)) ? 1 : 0;
;       }
;       const bool sel = (rank < 16) && (sc >= 0.f);
.LBB0_715:
	v_readlane_b32 s80, v254, 23
	v_mov_b32_e32 v4, v0
	v_readlane_b32 s81, v254, 24
	s_and_saveexec_b64 s[70:71], s[80:81]
	ds_read_b32 v4, v3
	s_or_b64 exec, exec, s[70:71]
	s_waitcnt lgkmcnt(0)
	v_sub_u32_e32 v6, 63, v155
	v_mov_b32_e32 v7, v4
	v_mov_b32_e32 v5, 0
	v_readlane_b32 s71, v4, 0
	s_mov_b32 s70, 63
	v_readlane_b32 s81, v4, 1
	s_mov_b32 s80, 62
	s_nop 1
	v_cmp_gt_i64_e32 vcc, s[70:71], v[6:7]
	v_readlane_b32 s71, v4, 2
	s_mov_b32 s70, 61
	v_addc_co_u32_e32 v5, vcc, 0, v5, vcc
	v_cmp_gt_i64_e32 vcc, s[80:81], v[6:7]
	v_readlane_b32 s81, v4, 3
	s_mov_b32 s80, 60
	v_addc_co_u32_e32 v5, vcc, 0, v5, vcc
	v_cmp_gt_i64_e32 vcc, s[70:71], v[6:7]
	v_readlane_b32 s71, v4, 4
	s_mov_b32 s70, 59
	v_addc_co_u32_e32 v5, vcc, 0, v5, vcc
	v_cmp_gt_i64_e32 vcc, s[80:81], v[6:7]
	v_readlane_b32 s81, v4, 5
	s_mov_b32 s80, 58
	v_addc_co_u32_e32 v5, vcc, 0, v5, vcc
	v_cmp_gt_i64_e32 vcc, s[70:71], v[6:7]
	v_readlane_b32 s71, v4, 6
	s_mov_b32 s70, 57
	v_addc_co_u32_e32 v5, vcc, 0, v5, vcc
	v_cmp_gt_i64_e32 vcc, s[80:81], v[6:7]
	v_readlane_b32 s81, v4, 7
	s_mov_b32 s80, 56
	v_addc_co_u32_e32 v5, vcc, 0, v5, vcc
	v_cmp_gt_i64_e32 vcc, s[70:71], v[6:7]
	v_readlane_b32 s71, v4, 8
	s_mov_b32 s70, 55
	v_addc_co_u32_e32 v5, vcc, 0, v5, vcc
	v_cmp_gt_i64_e32 vcc, s[80:81], v[6:7]
	v_readlane_b32 s81, v4, 9
	s_mov_b32 s80, 54
	v_addc_co_u32_e32 v5, vcc, 0, v5, vcc
	v_cmp_gt_i64_e32 vcc, s[70:71], v[6:7]
	v_readlane_b32 s71, v4, 10
	s_mov_b32 s70, 53
	v_addc_co_u32_e32 v5, vcc, 0, v5, vcc
	v_cmp_gt_i64_e32 vcc, s[80:81], v[6:7]
	v_readlane_b32 s81, v4, 11
	s_mov_b32 s80, 52
	v_addc_co_u32_e32 v5, vcc, 0, v5, vcc
	v_cmp_gt_i64_e32 vcc, s[70:71], v[6:7]
	v_readlane_b32 s71, v4, 12
	s_mov_b32 s70, 51
	v_addc_co_u32_e32 v5, vcc, 0, v5, vcc
	v_cmp_gt_i64_e32 vcc, s[80:81], v[6:7]
	v_readlane_b32 s81, v4, 13
	s_mov_b32 s80, 50
	v_addc_co_u32_e32 v5, vcc, 0, v5, vcc
	v_cmp_gt_i64_e32 vcc, s[70:71], v[6:7]
	v_readlane_b32 s71, v4, 14
	s_mov_b32 s70, 49
	v_addc_co_u32_e32 v5, vcc, 0, v5, vcc
	v_cmp_gt_i64_e32 vcc, s[80:81], v[6:7]
	v_readlane_b32 s81, v4, 15
	s_mov_b32 s80, 48
	v_addc_co_u32_e32 v5, vcc, 0, v5, vcc
	v_cmp_gt_i64_e32 vcc, s[70:71], v[6:7]
	v_readlane_b32 s71, v4, 16
	s_mov_b32 s70, 47
	v_addc_co_u32_e32 v5, vcc, 0, v5, vcc
	v_cmp_gt_i64_e32 vcc, s[80:81], v[6:7]
	v_readlane_b32 s81, v4, 17
	s_mov_b32 s80, 46
	v_addc_co_u32_e32 v5, vcc, 0, v5, vcc
	v_cmp_gt_i64_e32 vcc, s[70:71], v[6:7]
	v_readlane_b32 s71, v4, 18
	s_mov_b32 s70, 45
	v_addc_co_u32_e32 v5, vcc, 0, v5, vcc
	v_cmp_gt_i64_e32 vcc, s[80:81], v[6:7]
	v_readlane_b32 s81, v4, 19
	s_mov_b32 s80, 44
	v_addc_co_u32_e32 v5, vcc, 0, v5, vcc
	v_cmp_gt_i64_e32 vcc, s[70:71], v[6:7]
	v_readlane_b32 s71, v4, 20
	s_mov_b32 s70, 43
	v_addc_co_u32_e32 v5, vcc, 0, v5, vcc
	v_cmp_gt_i64_e32 vcc, s[80:81], v[6:7]
	v_readlane_b32 s81, v4, 21
	s_mov_b32 s80, 42
	v_addc_co_u32_e32 v5, vcc, 0, v5, vcc
	v_cmp_gt_i64_e32 vcc, s[70:71], v[6:7]
	v_readlane_b32 s71, v4, 22
	s_mov_b32 s70, 41
	v_addc_co_u32_e32 v5, vcc, 0, v5, vcc
	v_cmp_gt_i64_e32 vcc, s[80:81], v[6:7]
	v_readlane_b32 s81, v4, 23
	s_mov_b32 s80, 40
	v_addc_co_u32_e32 v5, vcc, 0, v5, vcc
	v_cmp_gt_i64_e32 vcc, s[70:71], v[6:7]
	v_readlane_b32 s71, v4, 24
	s_mov_b32 s70, 39
	v_addc_co_u32_e32 v5, vcc, 0, v5, vcc
	v_cmp_gt_i64_e32 vcc, s[80:81], v[6:7]
	v_readlane_b32 s81, v4, 25
	s_mov_b32 s80, 38
	v_addc_co_u32_e32 v5, vcc, 0, v5, vcc
	v_cmp_gt_i64_e32 vcc, s[70:71], v[6:7]
	v_readlane_b32 s71, v4, 26
	s_mov_b32 s70, 37
	v_addc_co_u32_e32 v5, vcc, 0, v5, vcc
	v_cmp_gt_i64_e32 vcc, s[80:81], v[6:7]
	v_readlane_b32 s81, v4, 27
	s_mov_b32 s80, 36
	v_addc_co_u32_e32 v5, vcc, 0, v5, vcc
	v_cmp_gt_i64_e32 vcc, s[70:71], v[6:7]
	v_readlane_b32 s71, v4, 28
	s_mov_b32 s70, 35
	v_addc_co_u32_e32 v5, vcc, 0, v5, vcc
	v_cmp_gt_i64_e32 vcc, s[80:81], v[6:7]
	v_readlane_b32 s81, v4, 29
	s_mov_b32 s80, 34
	v_addc_co_u32_e32 v5, vcc, 0, v5, vcc
	v_cmp_gt_i64_e32 vcc, s[70:71], v[6:7]
	v_readlane_b32 s71, v4, 30
	s_mov_b32 s70, 33
	v_addc_co_u32_e32 v5, vcc, 0, v5, vcc
	v_cmp_gt_i64_e32 vcc, s[80:81], v[6:7]
	v_readlane_b32 s81, v4, 31
	s_mov_b32 s80, 32
	v_addc_co_u32_e32 v5, vcc, 0, v5, vcc
	v_cmp_gt_i64_e32 vcc, s[70:71], v[6:7]
	v_readlane_b32 s71, v4, 32
	s_mov_b32 s70, 31
	v_addc_co_u32_e32 v5, vcc, 0, v5, vcc
	v_cmp_gt_i64_e32 vcc, s[80:81], v[6:7]
	v_readlane_b32 s81, v4, 33
; DI void nsa_item(const Params& p, int l_, int item, char* lds, int dry) {
;     ...
;       int rank = 0;
; #pragma unroll
;       for (int i = 0; i < 64; ++i) {
;         const float si = __int_as_float(__builtin_amdgcn_readlane(__float_as_int(sc), i));
;         rank += ((si > sc) || (si == sc && i < j)) ? 1 : 0;
;       }
;       const bool sel = (rank < 16) && (sc >= 0.f);
;       const u64 mk = __ballot(sel);
;       if (lane == 0) selm[q] = mk;
;       uni |= mk;
	s_mov_b32 s80, 30
	v_addc_co_u32_e32 v5, vcc, 0, v5, vcc
	v_cmp_gt_i64_e32 vcc, s[70:71], v[6:7]
	v_readlane_b32 s71, v4, 34
	s_mov_b32 s70, 29
	v_addc_co_u32_e32 v5, vcc, 0, v5, vcc
	v_cmp_gt_i64_e32 vcc, s[80:81], v[6:7]
	v_readlane_b32 s81, v4, 35
	s_mov_b32 s80, 28
	v_addc_co_u32_e32 v5, vcc, 0, v5, vcc
	v_cmp_gt_i64_e32 vcc, s[70:71], v[6:7]
	v_readlane_b32 s71, v4, 36
	s_mov_b32 s70, 27
	v_addc_co_u32_e32 v5, vcc, 0, v5, vcc
	v_cmp_gt_i64_e32 vcc, s[80:81], v[6:7]
	v_readlane_b32 s81, v4, 37
	s_mov_b32 s80, 26
	v_addc_co_u32_e32 v5, vcc, 0, v5, vcc
	v_cmp_gt_i64_e32 vcc, s[70:71], v[6:7]
	v_readlane_b32 s71, v4, 38
	s_mov_b32 s70, 25
	v_addc_co_u32_e32 v5, vcc, 0, v5, vcc
	v_cmp_gt_i64_e32 vcc, s[80:81], v[6:7]
	v_readlane_b32 s81, v4, 39
	s_mov_b32 s80, 24
	v_addc_co_u32_e32 v5, vcc, 0, v5, vcc
	v_cmp_gt_i64_e32 vcc, s[70:71], v[6:7]
	v_readlane_b32 s71, v4, 40
	s_mov_b32 s70, 23
	v_addc_co_u32_e32 v5, vcc, 0, v5, vcc
	v_cmp_gt_i64_e32 vcc, s[80:81], v[6:7]
	v_readlane_b32 s81, v4, 41
	s_mov_b32 s80, 22
	v_addc_co_u32_e32 v5, vcc, 0, v5, vcc
	v_cmp_gt_i64_e32 vcc, s[70:71], v[6:7]
	v_readlane_b32 s71, v4, 42
	s_mov_b32 s70, 21
	v_addc_co_u32_e32 v5, vcc, 0, v5, vcc
	v_cmp_gt_i64_e32 vcc, s[80:81], v[6:7]
	v_readlane_b32 s81, v4, 43
	s_mov_b32 s80, 20
	v_addc_co_u32_e32 v5, vcc, 0, v5, vcc
	v_cmp_gt_i64_e32 vcc, s[70:71], v[6:7]
	v_readlane_b32 s71, v4, 44
	s_mov_b32 s70, 19
	v_addc_co_u32_e32 v5, vcc, 0, v5, vcc
	v_cmp_gt_i64_e32 vcc, s[80:81], v[6:7]
	v_readlane_b32 s81, v4, 45
	s_mov_b32 s80, 18
	v_addc_co_u32_e32 v5, vcc, 0, v5, vcc
	v_cmp_gt_i64_e32 vcc, s[70:71], v[6:7]
	v_readlane_b32 s71, v4, 46
	s_mov_b32 s70, 17
	v_addc_co_u32_e32 v5, vcc, 0, v5, vcc
	v_cmp_gt_i64_e32 vcc, s[80:81], v[6:7]
	v_readlane_b32 s81, v4, 47
	s_mov_b32 s80, 16
	v_addc_co_u32_e32 v5, vcc, 0, v5, vcc
	v_cmp_gt_i64_e32 vcc, s[70:71], v[6:7]
	v_readlane_b32 s71, v4, 48
	s_mov_b32 s70, 15
	v_addc_co_u32_e32 v5, vcc, 0, v5, vcc
	v_cmp_gt_i64_e32 vcc, s[80:81], v[6:7]
	v_readlane_b32 s81, v4, 49
	s_mov_b32 s80, 14
	v_addc_co_u32_e32 v5, vcc, 0, v5, vcc
	v_cmp_gt_i64_e32 vcc, s[70:71], v[6:7]
	v_readlane_b32 s71, v4, 50
	s_mov_b32 s70, 13
	v_addc_co_u32_e32 v5, vcc, 0, v5, vcc
	v_cmp_gt_i64_e32 vcc, s[80:81], v[6:7]
	v_readlane_b32 s81, v4, 51
	s_mov_b32 s80, 12
	v_addc_co_u32_e32 v5, vcc, 0, v5, vcc
	v_cmp_gt_i64_e32 vcc, s[70:71], v[6:7]
	v_readlane_b32 s71, v4, 52
	s_mov_b32 s70, 11
	v_addc_co_u32_e32 v5, vcc, 0, v5, vcc
	v_cmp_gt_i64_e32 vcc, s[80:81], v[6:7]
	v_readlane_b32 s81, v4, 53
	s_mov_b32 s80, 10
	v_addc_co_u32_e32 v5, vcc, 0, v5, vcc
	v_cmp_gt_i64_e32 vcc, s[70:71], v[6:7]
	v_readlane_b32 s71, v4, 54
	s_mov_b32 s70, 9
	v_addc_co_u32_e32 v5, vcc, 0, v5, vcc
	v_cmp_gt_i64_e32 vcc, s[80:81], v[6:7]
	v_readlane_b32 s81, v4, 55
	s_mov_b32 s80, 8
	v_addc_co_u32_e32 v5, vcc, 0, v5, vcc
	v_cmp_gt_i64_e32 vcc, s[70:71], v[6:7]
	v_readlane_b32 s71, v4, 56
	s_mov_b32 s70, 7
	v_addc_co_u32_e32 v5, vcc, 0, v5, vcc
	v_cmp_gt_i64_e32 vcc, s[80:81], v[6:7]
	v_readlane_b32 s81, v4, 57
	s_mov_b32 s80, 6
	v_addc_co_u32_e32 v5, vcc, 0, v5, vcc
	v_cmp_gt_i64_e32 vcc, s[70:71], v[6:7]
	v_readlane_b32 s71, v4, 58
	s_mov_b32 s70, 5
	v_addc_co_u32_e32 v5, vcc, 0, v5, vcc
	v_cmp_gt_i64_e32 vcc, s[80:81], v[6:7]
	v_readlane_b32 s81, v4, 59
	s_mov_b32 s80, 4
	v_addc_co_u32_e32 v5, vcc, 0, v5, vcc
	v_cmp_gt_i64_e32 vcc, s[70:71], v[6:7]
	v_readlane_b32 s71, v4, 60
	s_mov_b32 s70, 3
	v_addc_co_u32_e32 v5, vcc, 0, v5, vcc
	v_cmp_gt_i64_e32 vcc, s[80:81], v[6:7]
	v_readlane_b32 s81, v4, 61
	s_mov_b32 s80, 2
	v_addc_co_u32_e32 v5, vcc, 0, v5, vcc
	v_cmp_gt_i64_e32 vcc, s[70:71], v[6:7]
	v_readlane_b32 s71, v4, 62
	s_mov_b32 s70, 1
	v_addc_co_u32_e32 v5, vcc, 0, v5, vcc
	v_cmp_gt_i64_e32 vcc, s[80:81], v[6:7]
	v_readlane_b32 s81, v4, 63
	s_mov_b32 s80, 0
	v_addc_co_u32_e32 v5, vcc, 0, v5, vcc
	v_cmp_gt_i64_e32 vcc, s[70:71], v[6:7]
	s_nop 1
	v_addc_co_u32_e32 v5, vcc, 0, v5, vcc
	v_cmp_gt_i64_e32 vcc, s[80:81], v[6:7]
	s_nop 1
	v_addc_co_u32_e32 v5, vcc, 0, v5, vcc
	v_cmp_le_f32_e64 s[70:71], 0, v4
	v_cmp_gt_u32_e32 vcc, 16, v5
	s_nop 1
	s_and_b64 s[70:71], vcc, s[70:71]
	v_cndmask_b32_e64 v4, 0, 1, s[70:71]
	v_cmp_ne_u32_e64 s[70:71], 0, v4
	s_and_saveexec_b64 vcc, s[72:73]
	s_cbranch_execz .LBB0_714
	v_add_u32_e32 v4, s78, v2
	v_mov_b64_e32 v[6:7], s[70:71]
	ds_write_b64 v4, v[6:7]
	s_branch .LBB0_714
